# P7 epilogue: the eight per-row-group rsq2 loads issued together, y stores no longer drained between groups
# speedup vs baseline: 1.0048x; 1.0048x over previous
.LBB0_1109:
	v_lshlrev_b64 v[144:145], 2, v[224:225]
	v_lshl_add_u64 v[8:9], s[20:21], 0, v[144:145]
	v_lshl_add_u64 v[146:147], v[222:223], 2, s[10:11]
	global_load_dwordx4 v[4:7], v[8:9], off offset:16
	global_load_dwordx4 v[12:15], v[8:9], off
	s_waitcnt lgkmcnt(0)
	global_load_dwordx4 v[0:3], v[8:9], off offset:528
	s_nop 0
	global_load_dwordx4 v[8:11], v[8:9], off offset:512
	v_lshl_add_u64 v[150:151], v[220:221], 2, s[10:11]
	global_load_dword v160, v[146:147], off sc1
	v_lshl_add_u64 v[168:169], v[220:221], 2, s[10:11]
	global_load_dword v161, v[168:169], off sc1
	v_lshl_add_u64 v[170:171], v[218:219], 2, s[10:11]
	global_load_dword v162, v[170:171], off sc1
	v_lshl_add_u64 v[172:173], v[216:217], 2, s[10:11]
	global_load_dword v163, v[172:173], off sc1
	v_lshl_add_u64 v[174:175], v[214:215], 2, s[10:11]
	global_load_dword v164, v[174:175], off sc1
	v_lshl_add_u64 v[176:177], v[212:213], 2, s[10:11]
	global_load_dword v165, v[176:177], off sc1
	v_lshl_add_u64 v[178:179], v[210:211], 2, s[10:11]
	global_load_dword v166, v[178:179], off sc1
	v_lshl_add_u64 v[180:181], v[208:209], 2, s[10:11]
	global_load_dword v167, v[180:181], off sc1
	v_lshlrev_b64 v[146:147], 12, v[222:223]
	v_lshl_add_u64 v[146:147], s[22:23], 0, v[146:147]
	v_lshl_add_u64 v[146:147], v[146:147], 0, v[144:145]
	s_and_b64 vcc, exec, s[4:5]
	s_mov_b64 s[2:3], -1
	s_waitcnt vmcnt(0)
	v_mov_b32_e32 v148, v160
	v_fmamk_f32 v148, v148, 0x3a800000, v234
	v_rsq_f32_e32 v148, v148
	s_nop 0
	v_pk_mul_f32 v[126:127], v[126:127], v[148:149] op_sel_hi:[1,0]
	v_pk_mul_f32 v[124:125], v[124:125], v[148:149] op_sel_hi:[1,0]
	v_pk_mul_f32 v[122:123], v[122:123], v[148:149] op_sel_hi:[1,0]
	v_pk_mul_f32 v[120:121], v[120:121], v[148:149] op_sel_hi:[1,0]
	v_pk_mul_f32 v[152:153], v[118:119], v[148:149] op_sel_hi:[1,0]
	v_pk_mul_f32 v[154:155], v[116:117], v[148:149] op_sel_hi:[1,0]
	v_pk_mul_f32 v[156:157], v[114:115], v[148:149] op_sel_hi:[1,0]
	v_pk_mul_f32 v[148:149], v[112:113], v[148:149] op_sel_hi:[1,0]
	v_pk_mul_f32 v[114:115], v[14:15], v[126:127]
	v_pk_mul_f32 v[112:113], v[12:13], v[124:125]
	v_pk_mul_f32 v[118:119], v[6:7], v[122:123]
	v_pk_mul_f32 v[116:117], v[4:5], v[120:121]
	v_pk_mul_f32 v[122:123], v[10:11], v[152:153]
	v_pk_mul_f32 v[120:121], v[8:9], v[154:155]
	v_pk_mul_f32 v[126:127], v[2:3], v[156:157]
	v_pk_mul_f32 v[124:125], v[0:1], v[148:149]
	global_store_dwordx4 v[146:147], v[112:115], off
	global_store_dwordx4 v[146:147], v[116:119], off offset:16
	global_store_dwordx4 v[146:147], v[120:123], off offset:512
	global_store_dwordx4 v[146:147], v[124:127], off offset:528
	v_mov_b32_e32 v114, v161
	v_lshlrev_b64 v[112:113], 12, v[220:221]
	v_lshl_add_u64 v[112:113], s[22:23], 0, v[112:113]
	v_lshl_add_u64 v[112:113], v[112:113], 0, v[144:145]
	v_lshl_add_u64 v[116:117], v[218:219], 2, s[10:11]
	v_fmamk_f32 v114, v114, 0x3a800000, v234
	v_rsq_f32_e32 v114, v114
	s_nop 0
	v_pk_mul_f32 v[110:111], v[110:111], v[114:115] op_sel_hi:[1,0]
	v_pk_mul_f32 v[108:109], v[108:109], v[114:115] op_sel_hi:[1,0]
	v_pk_mul_f32 v[106:107], v[106:107], v[114:115] op_sel_hi:[1,0]
	v_pk_mul_f32 v[104:105], v[104:105], v[114:115] op_sel_hi:[1,0]
	v_pk_mul_f32 v[118:119], v[102:103], v[114:115] op_sel_hi:[1,0]
	v_pk_mul_f32 v[120:121], v[100:101], v[114:115] op_sel_hi:[1,0]
	v_pk_mul_f32 v[122:123], v[98:99], v[114:115] op_sel_hi:[1,0]
	v_pk_mul_f32 v[114:115], v[96:97], v[114:115] op_sel_hi:[1,0]
	v_pk_mul_f32 v[98:99], v[14:15], v[110:111]
	v_pk_mul_f32 v[96:97], v[12:13], v[108:109]
	v_pk_mul_f32 v[102:103], v[6:7], v[106:107]
	v_pk_mul_f32 v[100:101], v[4:5], v[104:105]
	v_pk_mul_f32 v[106:107], v[10:11], v[118:119]
	v_pk_mul_f32 v[104:105], v[8:9], v[120:121]
	v_pk_mul_f32 v[110:111], v[2:3], v[122:123]
	v_pk_mul_f32 v[108:109], v[0:1], v[114:115]
	global_store_dwordx4 v[112:113], v[96:99], off
	global_store_dwordx4 v[112:113], v[100:103], off offset:16
	global_store_dwordx4 v[112:113], v[104:107], off offset:512
	global_store_dwordx4 v[112:113], v[108:111], off offset:528
	v_mov_b32_e32 v98, v162
	v_lshlrev_b64 v[96:97], 12, v[218:219]
	v_lshl_add_u64 v[96:97], s[22:23], 0, v[96:97]
	v_lshl_add_u64 v[96:97], v[96:97], 0, v[144:145]
	v_lshl_add_u64 v[100:101], v[216:217], 2, s[10:11]
	v_fmamk_f32 v98, v98, 0x3a800000, v234
	v_rsq_f32_e32 v98, v98
	s_nop 0
	v_pk_mul_f32 v[94:95], v[94:95], v[98:99] op_sel_hi:[1,0]
	v_pk_mul_f32 v[92:93], v[92:93], v[98:99] op_sel_hi:[1,0]
	v_pk_mul_f32 v[90:91], v[90:91], v[98:99] op_sel_hi:[1,0]
	v_pk_mul_f32 v[88:89], v[88:89], v[98:99] op_sel_hi:[1,0]
	v_pk_mul_f32 v[102:103], v[86:87], v[98:99] op_sel_hi:[1,0]
	v_pk_mul_f32 v[104:105], v[84:85], v[98:99] op_sel_hi:[1,0]
	v_pk_mul_f32 v[106:107], v[82:83], v[98:99] op_sel_hi:[1,0]
	v_pk_mul_f32 v[98:99], v[80:81], v[98:99] op_sel_hi:[1,0]
	v_pk_mul_f32 v[82:83], v[14:15], v[94:95]
	v_pk_mul_f32 v[80:81], v[12:13], v[92:93]
	v_pk_mul_f32 v[86:87], v[6:7], v[90:91]
	v_pk_mul_f32 v[84:85], v[4:5], v[88:89]
	v_pk_mul_f32 v[90:91], v[10:11], v[102:103]
	v_pk_mul_f32 v[88:89], v[8:9], v[104:105]
	v_pk_mul_f32 v[94:95], v[2:3], v[106:107]
	v_pk_mul_f32 v[92:93], v[0:1], v[98:99]
	global_store_dwordx4 v[96:97], v[80:83], off
	global_store_dwordx4 v[96:97], v[84:87], off offset:16
	global_store_dwordx4 v[96:97], v[88:91], off offset:512
	global_store_dwordx4 v[96:97], v[92:95], off offset:528
	v_mov_b32_e32 v82, v163
	v_lshlrev_b64 v[80:81], 12, v[216:217]
	v_lshl_add_u64 v[80:81], s[22:23], 0, v[80:81]
	v_lshl_add_u64 v[80:81], v[80:81], 0, v[144:145]
	v_lshl_add_u64 v[84:85], v[214:215], 2, s[10:11]
	v_fmamk_f32 v82, v82, 0x3a800000, v234
	v_rsq_f32_e32 v82, v82
	s_nop 0
	v_pk_mul_f32 v[78:79], v[78:79], v[82:83] op_sel_hi:[1,0]
	v_pk_mul_f32 v[76:77], v[76:77], v[82:83] op_sel_hi:[1,0]
	v_pk_mul_f32 v[74:75], v[74:75], v[82:83] op_sel_hi:[1,0]
	v_pk_mul_f32 v[72:73], v[72:73], v[82:83] op_sel_hi:[1,0]
	v_pk_mul_f32 v[86:87], v[70:71], v[82:83] op_sel_hi:[1,0]
	v_pk_mul_f32 v[88:89], v[68:69], v[82:83] op_sel_hi:[1,0]
	v_pk_mul_f32 v[90:91], v[66:67], v[82:83] op_sel_hi:[1,0]
	v_pk_mul_f32 v[82:83], v[64:65], v[82:83] op_sel_hi:[1,0]
	v_pk_mul_f32 v[66:67], v[14:15], v[78:79]
	v_pk_mul_f32 v[64:65], v[12:13], v[76:77]
	v_pk_mul_f32 v[70:71], v[6:7], v[74:75]
	v_pk_mul_f32 v[68:69], v[4:5], v[72:73]
	v_pk_mul_f32 v[74:75], v[10:11], v[86:87]
	v_pk_mul_f32 v[72:73], v[8:9], v[88:89]
	v_pk_mul_f32 v[78:79], v[2:3], v[90:91]
	v_pk_mul_f32 v[76:77], v[0:1], v[82:83]
	global_store_dwordx4 v[80:81], v[64:67], off
	global_store_dwordx4 v[80:81], v[68:71], off offset:16
	global_store_dwordx4 v[80:81], v[72:75], off offset:512
	global_store_dwordx4 v[80:81], v[76:79], off offset:528
	v_mov_b32_e32 v66, v164
	v_lshlrev_b64 v[64:65], 12, v[214:215]
	v_lshl_add_u64 v[64:65], s[22:23], 0, v[64:65]
	v_lshl_add_u64 v[64:65], v[64:65], 0, v[144:145]
	v_lshl_add_u64 v[68:69], v[212:213], 2, s[10:11]
	v_fmamk_f32 v66, v66, 0x3a800000, v234
	v_rsq_f32_e32 v66, v66
	s_nop 0
	v_pk_mul_f32 v[62:63], v[62:63], v[66:67] op_sel_hi:[1,0]
	v_pk_mul_f32 v[60:61], v[60:61], v[66:67] op_sel_hi:[1,0]
	v_pk_mul_f32 v[58:59], v[58:59], v[66:67] op_sel_hi:[1,0]
	v_pk_mul_f32 v[56:57], v[56:57], v[66:67] op_sel_hi:[1,0]
	v_pk_mul_f32 v[70:71], v[54:55], v[66:67] op_sel_hi:[1,0]
	v_pk_mul_f32 v[72:73], v[52:53], v[66:67] op_sel_hi:[1,0]
	v_pk_mul_f32 v[74:75], v[50:51], v[66:67] op_sel_hi:[1,0]
	v_pk_mul_f32 v[66:67], v[48:49], v[66:67] op_sel_hi:[1,0]
	v_pk_mul_f32 v[50:51], v[14:15], v[62:63]
	v_pk_mul_f32 v[48:49], v[12:13], v[60:61]
	v_pk_mul_f32 v[54:55], v[6:7], v[58:59]
	v_pk_mul_f32 v[52:53], v[4:5], v[56:57]
	v_pk_mul_f32 v[58:59], v[10:11], v[70:71]
	v_pk_mul_f32 v[56:57], v[8:9], v[72:73]
	v_pk_mul_f32 v[62:63], v[2:3], v[74:75]
	v_pk_mul_f32 v[60:61], v[0:1], v[66:67]
	global_store_dwordx4 v[64:65], v[48:51], off
	global_store_dwordx4 v[64:65], v[52:55], off offset:16
	global_store_dwordx4 v[64:65], v[56:59], off offset:512
	global_store_dwordx4 v[64:65], v[60:63], off offset:528
	v_mov_b32_e32 v50, v165
	v_lshlrev_b64 v[48:49], 12, v[212:213]
	v_lshl_add_u64 v[48:49], s[22:23], 0, v[48:49]
	v_lshl_add_u64 v[48:49], v[48:49], 0, v[144:145]
	v_lshl_add_u64 v[52:53], v[210:211], 2, s[10:11]
	v_fmamk_f32 v50, v50, 0x3a800000, v234
	v_rsq_f32_e32 v50, v50
	s_nop 0
	v_pk_mul_f32 v[46:47], v[46:47], v[50:51] op_sel_hi:[1,0]
	v_pk_mul_f32 v[44:45], v[44:45], v[50:51] op_sel_hi:[1,0]
	v_pk_mul_f32 v[42:43], v[42:43], v[50:51] op_sel_hi:[1,0]
	v_pk_mul_f32 v[40:41], v[40:41], v[50:51] op_sel_hi:[1,0]
	v_pk_mul_f32 v[54:55], v[38:39], v[50:51] op_sel_hi:[1,0]
	v_pk_mul_f32 v[56:57], v[36:37], v[50:51] op_sel_hi:[1,0]
	v_pk_mul_f32 v[58:59], v[34:35], v[50:51] op_sel_hi:[1,0]
	v_pk_mul_f32 v[50:51], v[32:33], v[50:51] op_sel_hi:[1,0]
	v_pk_mul_f32 v[34:35], v[14:15], v[46:47]
	v_pk_mul_f32 v[32:33], v[12:13], v[44:45]
	v_pk_mul_f32 v[38:39], v[6:7], v[42:43]
	v_pk_mul_f32 v[36:37], v[4:5], v[40:41]
	v_pk_mul_f32 v[42:43], v[10:11], v[54:55]
	v_pk_mul_f32 v[40:41], v[8:9], v[56:57]
	v_pk_mul_f32 v[46:47], v[2:3], v[58:59]
	v_pk_mul_f32 v[44:45], v[0:1], v[50:51]
	global_store_dwordx4 v[48:49], v[32:35], off
	global_store_dwordx4 v[48:49], v[36:39], off offset:16
	global_store_dwordx4 v[48:49], v[40:43], off offset:512
	global_store_dwordx4 v[48:49], v[44:47], off offset:528
	v_mov_b32_e32 v34, v166
	v_lshlrev_b64 v[32:33], 12, v[210:211]
	v_lshl_add_u64 v[32:33], s[22:23], 0, v[32:33]
	v_lshl_add_u64 v[42:43], v[32:33], 0, v[144:145]
	v_lshl_add_u64 v[40:41], v[208:209], 2, s[10:11]
	v_fmamk_f32 v34, v34, 0x3a800000, v234
	v_rsq_f32_e32 v34, v34
	s_nop 0
	v_pk_mul_f32 v[30:31], v[30:31], v[34:35] op_sel_hi:[1,0]
	v_pk_mul_f32 v[28:29], v[28:29], v[34:35] op_sel_hi:[1,0]
	v_pk_mul_f32 v[32:33], v[26:27], v[34:35] op_sel_hi:[1,0]
	v_pk_mul_f32 v[36:37], v[24:25], v[34:35] op_sel_hi:[1,0]
	v_pk_mul_f32 v[38:39], v[136:137], v[34:35] op_sel_hi:[1,0]
	v_pk_mul_f32 v[44:45], v[138:139], v[34:35] op_sel_hi:[1,0]
	v_pk_mul_f32 v[46:47], v[140:141], v[34:35] op_sel_hi:[1,0]
	v_pk_mul_f32 v[48:49], v[142:143], v[34:35] op_sel_hi:[1,0]
	v_pk_mul_f32 v[26:27], v[14:15], v[30:31]
	v_pk_mul_f32 v[24:25], v[12:13], v[28:29]
	v_pk_mul_f32 v[30:31], v[6:7], v[32:33]
	v_pk_mul_f32 v[28:29], v[4:5], v[36:37]
	v_pk_mul_f32 v[34:35], v[10:11], v[38:39]
	v_pk_mul_f32 v[32:33], v[8:9], v[44:45]
	v_pk_mul_f32 v[38:39], v[2:3], v[46:47]
	v_pk_mul_f32 v[36:37], v[0:1], v[48:49]
	global_store_dwordx4 v[42:43], v[24:27], off
	global_store_dwordx4 v[42:43], v[28:31], off offset:16
	global_store_dwordx4 v[42:43], v[32:35], off offset:512
	global_store_dwordx4 v[42:43], v[36:39], off offset:528
	v_mov_b32_e32 v26, v167
	v_lshlrev_b64 v[24:25], 12, v[208:209]
	v_lshl_add_u64 v[24:25], s[22:23], 0, v[24:25]
	v_lshl_add_u64 v[24:25], v[24:25], 0, v[144:145]
	v_fmamk_f32 v26, v26, 0x3a800000, v234
	v_rsq_f32_e32 v26, v26
	s_nop 0
	v_pk_mul_f32 v[16:17], v[16:17], v[26:27] op_sel_hi:[1,0]
	v_pk_mul_f32 v[18:19], v[18:19], v[26:27] op_sel_hi:[1,0]
	v_pk_mul_f32 v[20:21], v[20:21], v[26:27] op_sel_hi:[1,0]
	v_pk_mul_f32 v[22:23], v[22:23], v[26:27] op_sel_hi:[1,0]
	v_pk_mul_f32 v[28:29], v[128:129], v[26:27] op_sel_hi:[1,0]
	v_pk_mul_f32 v[30:31], v[130:131], v[26:27] op_sel_hi:[1,0]
	v_pk_mul_f32 v[32:33], v[132:133], v[26:27] op_sel_hi:[1,0]
	v_pk_mul_f32 v[26:27], v[134:135], v[26:27] op_sel_hi:[1,0]
	v_pk_mul_f32 v[14:15], v[14:15], v[16:17]
	v_pk_mul_f32 v[12:13], v[12:13], v[18:19]
	v_pk_mul_f32 v[6:7], v[6:7], v[20:21]
	v_pk_mul_f32 v[4:5], v[4:5], v[22:23]
	v_pk_mul_f32 v[10:11], v[10:11], v[28:29]
	v_pk_mul_f32 v[8:9], v[8:9], v[30:31]
	v_pk_mul_f32 v[2:3], v[2:3], v[32:33]
	v_pk_mul_f32 v[0:1], v[0:1], v[26:27]
	global_store_dwordx4 v[24:25], v[12:15], off
	global_store_dwordx4 v[24:25], v[4:7], off offset:16
	global_store_dwordx4 v[24:25], v[8:11], off offset:512
	global_store_dwordx4 v[24:25], v[0:3], off offset:528
	s_cbranch_vccnz .LBB0_1032
	s_andn2_b64 vcc, exec, s[8:9]
	s_cbranch_vccnz .LBB0_1031
	s_barrier
	s_branch .LBB0_1031
